# MLA attention tile loop: rolling LDS fragment prefetch (K/V fragment re-loaded as soon as the MFMA that read its register has issued, 6 MFMAs ahead)
# speedup vs baseline: 1.0574x; 1.0057x over previous
; #define LAS __attribute__((address_space(3)))
; template <int DQK, int DV, bool FOX> ...
;     ...
;                 for (int g0 = 0; g0 < ND0; g0 += GB) { bf16x8 ka[GB], kb[GB];
; #pragma unroll
;                     for (int j = 0; j < GB; ++j) { const int c = 2 * (g0 + j) + h; const int co = ((c & ~7) | ((c ^ ksw) & 7)) * 16;
;                         ka[j] = *(const LAS bf16x8*)(b + kread0 + co); kb[j] = *(const LAS bf16x8*)(b + kread0 + 32 * KROW + co); }
;                     __builtin_amdgcn_sched_barrier(0);
; #pragma unroll
;                     for (int j = 0; j < GB; ++j) { p0 = __builtin_amdgcn_mfma_f32_32x32x16_bf16(ka[j], qf[g0 + j], p0, 0, 0, 0);
;                                                    p1 = __builtin_amdgcn_mfma_f32_32x32x16_bf16(kb[j], qf[g0 + j], p1, 0, 0, 0); }
;                     __builtin_amdgcn_sched_barrier(0); } }
;     ...
;             float rm = fmaxf(fmaxf(p0[0], p1[0]), p0[1]);
; #pragma unroll
;             for (int i = 1; i < 15; ++i) rm = fmaxf(fmaxf(rm, p1[i]), p0[i + 1]);
;             rm = fmaxf(rm, p1[15]);
;             { const auto rr_ = __builtin_amdgcn_permlane32_swap(__float_as_uint(rm), __float_as_uint(rm), false, false);
;               rm = fmaxf(__uint_as_float(rr_[0]), __uint_as_float(rr_[1])); }
;             const bool grow = rm > mloc + THR;
;             if (__any(grow)) {
;                 const float mnew = grow ? rm : mloc; const float al = __builtin_amdgcn_exp2f(mloc - mnew);
;                 lsum *= al; mref = grow ? (mnew + cqt) : mref; mloc = mnew;
;                 if (h == 0) wsf[r] = al;
;                 asm volatile("s_waitcnt lgkmcnt(0)" ::: "memory");
; #pragma unroll
;                 for (int g = 0; g < 4; ++g) { const f32x4 a4 = *(const LAS f32x4*)(wsf + 8 * g + 4 * h);
; #pragma unroll
;                     for (int cb = 0; cb < NCB; ++cb)
; #pragma unroll
;                         for (int e = 0; e < 4; ++e) o[cb][4 * g + e] *= a4[e]; }
.LBB0_723:
	s_mul_i32 s1, s6, 0xa100
	s_add_i32 s1, s1, 0
	v_mul_u32_u24_e32 v66, 0x180, v146
	v_add_u32_e32 v193, s1, v66
	v_add_u32_e32 v195, v193, v197
	v_add_u32_e32 v210, v193, v211
	v_add_u32_e32 v254, v193, v212
	v_add_u32_e32 v193, v193, v213
	ds_read_b128 v[66:69], v195
	ds_read_b128 v[70:73], v195 offset:12288
	ds_read_b128 v[234:237], v210
	ds_read_b128 v[238:241], v210 offset:12288
	ds_read_b128 v[242:245], v254
	ds_read_b128 v[246:249], v254 offset:12288
	ds_read_b128 v[250:253], v193
	ds_read_b128 v[214:217], v193 offset:12288
	s_waitcnt lgkmcnt(7)
	v_mfma_f32_32x32x16_bf16 v[82:97], v[66:69], v[98:101], 0
	s_waitcnt lgkmcnt(6)
	v_mfma_f32_32x32x16_bf16 v[66:81], v[70:73], v[98:101], 0
	s_waitcnt lgkmcnt(5)
	v_mfma_f32_32x32x16_bf16 v[82:97], v[234:237], v[102:105], v[82:97]
	ds_read_b128 v[234:237], v195 offset:128
	s_waitcnt lgkmcnt(5)
	v_mfma_f32_32x32x16_bf16 v[66:81], v[238:241], v[102:105], v[66:81]
	ds_read_b128 v[238:241], v195 offset:12416
	s_waitcnt lgkmcnt(5)
	v_mfma_f32_32x32x16_bf16 v[82:97], v[242:245], v[106:109], v[82:97]
	ds_read_b128 v[242:245], v210 offset:128
	s_waitcnt lgkmcnt(5)
	v_mfma_f32_32x32x16_bf16 v[66:81], v[246:249], v[106:109], v[66:81]
	ds_read_b128 v[246:249], v210 offset:12416
	s_waitcnt lgkmcnt(5)
	v_mfma_f32_32x32x16_bf16 v[82:97], v[250:253], v[110:113], v[82:97]
	ds_read_b128 v[250:253], v254 offset:128
	s_waitcnt lgkmcnt(5)
	v_mfma_f32_32x32x16_bf16 v[66:81], v[214:217], v[110:113], v[66:81]
	ds_read_b128 v[214:217], v254 offset:12416
	s_waitcnt lgkmcnt(5)
	v_mfma_f32_32x32x16_bf16 v[82:97], v[234:237], v[114:117], v[82:97]
	ds_read_b128 v[234:237], v193 offset:128
	s_waitcnt lgkmcnt(5)
	v_mfma_f32_32x32x16_bf16 v[66:81], v[238:241], v[114:117], v[66:81]
	ds_read_b128 v[238:241], v193 offset:12416
	s_waitcnt lgkmcnt(5)
	v_mfma_f32_32x32x16_bf16 v[82:97], v[242:245], v[118:121], v[82:97]
	ds_read_b128 v[242:245], v195 offset:256
	s_waitcnt lgkmcnt(5)
	v_mfma_f32_32x32x16_bf16 v[66:81], v[246:249], v[118:121], v[66:81]
	ds_read_b128 v[246:249], v195 offset:12544
	s_waitcnt lgkmcnt(5)
	v_mfma_f32_32x32x16_bf16 v[82:97], v[250:253], v[122:125], v[82:97]
	ds_read_b128 v[250:253], v210 offset:256
	s_waitcnt lgkmcnt(5)
	v_mfma_f32_32x32x16_bf16 v[66:81], v[214:217], v[122:125], v[66:81]
	ds_read_b128 v[214:217], v210 offset:12544
	s_waitcnt lgkmcnt(5)
	v_mfma_f32_32x32x16_bf16 v[82:97], v[234:237], v[126:129], v[82:97]
	ds_read_b128 v[234:237], v254 offset:256
	s_waitcnt lgkmcnt(5)
	v_mfma_f32_32x32x16_bf16 v[66:81], v[238:241], v[126:129], v[66:81]
	ds_read_b128 v[238:241], v254 offset:12544
	s_waitcnt lgkmcnt(5)
	v_mfma_f32_32x32x16_bf16 v[82:97], v[242:245], v[130:133], v[82:97]
	ds_read_b128 v[242:245], v193 offset:256
	s_waitcnt lgkmcnt(5)
	v_mfma_f32_32x32x16_bf16 v[66:81], v[246:249], v[130:133], v[66:81]
	ds_read_b128 v[246:249], v193 offset:12544
	s_waitcnt lgkmcnt(5)
	v_mfma_f32_32x32x16_bf16 v[82:97], v[250:253], v[134:137], v[82:97]
	s_waitcnt lgkmcnt(4)
	v_mfma_f32_32x32x16_bf16 v[66:81], v[214:217], v[134:137], v[66:81]
	s_waitcnt lgkmcnt(3)
	v_mfma_f32_32x32x16_bf16 v[82:97], v[234:237], v[138:141], v[82:97]
	s_waitcnt lgkmcnt(2)
	v_mfma_f32_32x32x16_bf16 v[66:81], v[238:241], v[138:141], v[66:81]
	s_waitcnt lgkmcnt(1)
	v_mfma_f32_32x32x16_bf16 v[82:97], v[242:245], v[142:145], v[82:97]
	s_waitcnt lgkmcnt(0)
	v_mfma_f32_32x32x16_bf16 v[66:81], v[246:249], v[142:145], v[66:81]
	s_nop 11
	v_max_f32_e32 v193, v66, v66
	v_max_f32_e32 v195, v82, v82
	v_max_f32_e32 v193, v195, v193
	v_max3_f32 v193, v193, v83, v67
	v_max3_f32 v193, v193, v84, v68
	v_max3_f32 v193, v193, v85, v69
	v_max3_f32 v193, v193, v86, v70
	v_max3_f32 v193, v193, v87, v71
	v_max3_f32 v193, v193, v88, v72
	v_max3_f32 v193, v193, v89, v73
	v_max3_f32 v193, v193, v90, v74
	v_max3_f32 v193, v193, v91, v75
	v_max3_f32 v193, v193, v92, v76
	v_max3_f32 v193, v193, v93, v77
	v_max3_f32 v193, v193, v94, v78
	v_max3_f32 v193, v193, v95, v79
	v_max3_f32 v193, v193, v96, v80
	v_max3_f32 v193, v193, v97, v81
	v_mov_b32_e32 v195, v193
	s_nop 1
	v_permlane32_swap_b32_e32 v193, v195
	v_max_f32_e32 v195, v195, v195
	v_max_f32_e32 v193, v193, v193
	v_max_f32_e32 v193, v193, v195
	v_add_f32_e32 v195, 0x40c00000, v233
	v_cmp_gt_f32_e32 vcc, v193, v195
	s_cbranch_vccz .LBB0_727
	s_nop 0
	v_cndmask_b32_e32 v210, v233, v193, vcc
	v_sub_f32_e32 v195, v233, v210
	v_exp_f32_e32 v195, v195
	s_and_saveexec_b64 s[2:3], s[12:13]
	ds_write_b32 v231, v195
	s_or_b64 exec, exec, s[2:3]
	s_waitcnt lgkmcnt(0)
	ds_read_b128 v[214:217], v230 offset:64
	ds_read_b128 v[234:237], v230 offset:96
	ds_read_b128 v[238:241], v230
	ds_read_b128 v[242:245], v230 offset:32
	v_add_f32_e32 v193, 0, v193
	v_mul_f32_e32 v232, v232, v195
	v_cndmask_b32_e32 v233, v233, v193, vcc
	s_waitcnt lgkmcnt(2)
	v_pk_mul_f32 v[64:65], v[64:65], v[236:237]
	v_pk_mul_f32 v[60:61], v[60:61], v[216:217]
	s_waitcnt lgkmcnt(0)
	v_pk_mul_f32 v[56:57], v[56:57], v[244:245]
	v_pk_mul_f32 v[52:53], v[52:53], v[240:241]
	v_pk_mul_f32 v[62:63], v[62:63], v[234:235]
	v_pk_mul_f32 v[58:59], v[58:59], v[214:215]
	v_pk_mul_f32 v[54:55], v[54:55], v[242:243]
	v_pk_mul_f32 v[50:51], v[50:51], v[238:239]
	v_pk_mul_f32 v[48:49], v[48:49], v[236:237]
	v_pk_mul_f32 v[44:45], v[44:45], v[216:217]
	v_pk_mul_f32 v[40:41], v[40:41], v[244:245]
	v_pk_mul_f32 v[36:37], v[36:37], v[240:241]
	v_pk_mul_f32 v[46:47], v[46:47], v[234:235]
	v_pk_mul_f32 v[42:43], v[42:43], v[214:215]
	v_pk_mul_f32 v[38:39], v[38:39], v[242:243]
	v_pk_mul_f32 v[34:35], v[34:35], v[238:239]
	v_pk_mul_f32 v[32:33], v[32:33], v[236:237]
	v_pk_mul_f32 v[28:29], v[28:29], v[216:217]
	v_pk_mul_f32 v[24:25], v[24:25], v[244:245]
	v_pk_mul_f32 v[20:21], v[20:21], v[240:241]
	v_pk_mul_f32 v[30:31], v[30:31], v[234:235]
	v_pk_mul_f32 v[26:27], v[26:27], v[214:215]
	v_pk_mul_f32 v[22:23], v[22:23], v[242:243]
	v_pk_mul_f32 v[18:19], v[18:19], v[238:239]
	v_pk_mul_f32 v[16:17], v[16:17], v[236:237]
	v_pk_mul_f32 v[12:13], v[12:13], v[216:217]
	v_pk_mul_f32 v[8:9], v[8:9], v[244:245]
	v_pk_mul_f32 v[4:5], v[4:5], v[240:241]
	v_pk_mul_f32 v[14:15], v[14:15], v[234:235]
	v_pk_mul_f32 v[10:11], v[10:11], v[214:215]
	v_pk_mul_f32 v[6:7], v[6:7], v[242:243]
	v_pk_mul_f32 v[2:3], v[2:3], v[238:239]
	s_branch .LBB0_728

; #define LAS __attribute__((address_space(3)))
; template <int DQK, int DV, bool FOX> ...
;     ...
;             float ps = 0.f; f32x2v ps2 = {0.f, 0.f};
; #pragma unroll
;             for (int i = 0; i < 16; i += 2) { const f32x2v ml = (f32x2v){mloc, mloc};
;                 const f32x2v a0 = (f32x2v){p0[i], p0[i + 1]} - ml, a1 = (f32x2v){p1[i], p1[i + 1]} - ml;
;                 f32x2v e0, e1; e0.x = __builtin_amdgcn_exp2f(a0.x); e0.y = __builtin_amdgcn_exp2f(a0.y); e1.x = __builtin_amdgcn_exp2f(a1.x); e1.y = __builtin_amdgcn_exp2f(a1.y);
;                 p0[i] = e0.x; p0[i + 1] = e0.y; p1[i] = e1.x; p1[i + 1] = e1.y; ps2 += e0 + e1; }
;             ps = ps2.x + ps2.y;
;             lsum += ps;
;             bf16x8 pa[4];
;             { u32x4 t0, t1, t2, t3;
;               t0.x = pg8::cvt_pk_bf16(p0[0], p0[1]); t0.y = pg8::cvt_pk_bf16(p0[2], p0[3]); t0.z = pg8::cvt_pk_bf16(p0[4], p0[5]); t0.w = pg8::cvt_pk_bf16(p0[6], p0[7]);
;               t1.x = pg8::cvt_pk_bf16(p0[8], p0[9]); t1.y = pg8::cvt_pk_bf16(p0[10], p0[11]); t1.z = pg8::cvt_pk_bf16(p0[12], p0[13]); t1.w = pg8::cvt_pk_bf16(p0[14], p0[15]);
;               t2.x = pg8::cvt_pk_bf16(p1[0], p1[1]); t2.y = pg8::cvt_pk_bf16(p1[2], p1[3]); t2.z = pg8::cvt_pk_bf16(p1[4], p1[5]); t2.w = pg8::cvt_pk_bf16(p1[6], p1[7]);
;               t3.x = pg8::cvt_pk_bf16(p1[8], p1[9]); t3.y = pg8::cvt_pk_bf16(p1[10], p1[11]); t3.z = pg8::cvt_pk_bf16(p1[12], p1[13]); t3.w = pg8::cvt_pk_bf16(p1[14], p1[15]);
;               pa[0] = __builtin_bit_cast(bf16x8, t0); pa[1] = __builtin_bit_cast(bf16x8, t1); pa[2] = __builtin_bit_cast(bf16x8, t2); pa[3] = __builtin_bit_cast(bf16x8, t3); }
; #pragma unroll
;             for (int cb = 0; cb < NCB; ++cb) { s16x4 lo[4], hi[4];
; #pragma unroll
;                 for (int ks = 0; ks < 4; ++ks) {
;                     if (FOX && cb == 0) { lo[ks] = vlo0[ks]; hi[ks] = vhi0[ks]; }
;                     else {
;                     lo[ks] = __builtin_bit_cast(s16x4, __builtin_amdgcn_ds_read_tr16_b64_v4i16((LAS s16x4*)(b + vread0 + cb * 4096 + ks * 1024)));
;                     hi[ks] = __builtin_bit_cast(s16x4, __builtin_amdgcn_ds_read_tr16_b64_v4i16((LAS s16x4*)(b + vread0 + cb * 4096 + ks * 1024 + 512))); } }
;                 __builtin_amdgcn_sched_barrier(0);
; #pragma unroll
.LBB0_728:
	v_pk_add_f32 v[82:83], v[82:83], v[210:211] op_sel_hi:[1,0] neg_lo:[0,1] neg_hi:[0,1]
	v_pk_add_f32 v[66:67], v[66:67], v[210:211] op_sel_hi:[1,0] neg_lo:[0,1] neg_hi:[0,1]
	v_exp_f32_e32 v82, v82
	v_exp_f32_e32 v83, v83
	v_exp_f32_e32 v214, v66
	v_exp_f32_e32 v215, v67
	v_pk_add_f32 v[66:67], v[84:85], v[210:211] op_sel_hi:[1,0] neg_lo:[0,1] neg_hi:[0,1]
	v_pk_add_f32 v[68:69], v[68:69], v[210:211] op_sel_hi:[1,0] neg_lo:[0,1] neg_hi:[0,1]
	v_exp_f32_e32 v84, v66
	v_exp_f32_e32 v85, v67
	v_exp_f32_e32 v216, v68
	v_exp_f32_e32 v217, v69
	v_pk_add_f32 v[86:87], v[86:87], v[210:211] op_sel_hi:[1,0] neg_lo:[0,1] neg_hi:[0,1]
	v_pk_add_f32 v[70:71], v[70:71], v[210:211] op_sel_hi:[1,0] neg_lo:[0,1] neg_hi:[0,1]
	v_exp_f32_e32 v86, v86
	v_exp_f32_e32 v87, v87
	v_exp_f32_e32 v234, v70
	v_exp_f32_e32 v235, v71
	v_pk_add_f32 v[70:71], v[88:89], v[210:211] op_sel_hi:[1,0] neg_lo:[0,1] neg_hi:[0,1]
	v_pk_add_f32 v[72:73], v[72:73], v[210:211] op_sel_hi:[1,0] neg_lo:[0,1] neg_hi:[0,1]
	v_exp_f32_e32 v70, v70
	v_exp_f32_e32 v71, v71
	v_exp_f32_e32 v88, v72
	v_exp_f32_e32 v89, v73
	v_pk_add_f32 v[72:73], v[90:91], v[210:211] op_sel_hi:[1,0] neg_lo:[0,1] neg_hi:[0,1]
	v_pk_add_f32 v[74:75], v[74:75], v[210:211] op_sel_hi:[1,0] neg_lo:[0,1] neg_hi:[0,1]
	v_pk_add_f32 v[66:67], v[82:83], v[214:215]
	v_exp_f32_e32 v72, v72
	v_exp_f32_e32 v73, v73
	v_exp_f32_e32 v90, v74
	v_exp_f32_e32 v91, v75
	v_pk_add_f32 v[74:75], v[92:93], v[210:211] op_sel_hi:[1,0] neg_lo:[0,1] neg_hi:[0,1]
	v_pk_add_f32 v[76:77], v[76:77], v[210:211] op_sel_hi:[1,0] neg_lo:[0,1] neg_hi:[0,1]
	v_pk_add_f32 v[66:67], v[66:67], 0 op_sel_hi:[1,0]
	v_pk_add_f32 v[68:69], v[84:85], v[216:217]
	v_exp_f32_e32 v74, v74
	v_exp_f32_e32 v75, v75
	v_exp_f32_e32 v92, v76
	v_exp_f32_e32 v93, v77
	v_pk_add_f32 v[66:67], v[68:69], v[66:67]
	v_pk_add_f32 v[68:69], v[86:87], v[234:235]
	s_nop 0
	v_pk_add_f32 v[66:67], v[68:69], v[66:67]
	v_pk_add_f32 v[68:69], v[70:71], v[88:89]
	s_nop 0
	v_pk_add_f32 v[66:67], v[68:69], v[66:67]
	v_pk_add_f32 v[68:69], v[72:73], v[90:91]
	s_nop 0
	v_pk_add_f32 v[66:67], v[68:69], v[66:67]
	v_pk_add_f32 v[68:69], v[74:75], v[92:93]
	s_nop 0
	v_pk_add_f32 v[236:237], v[68:69], v[66:67]
	v_pk_add_f32 v[66:67], v[94:95], v[210:211] op_sel_hi:[1,0] neg_lo:[0,1] neg_hi:[0,1]
	v_pk_add_f32 v[68:69], v[78:79], v[210:211] op_sel_hi:[1,0] neg_lo:[0,1] neg_hi:[0,1]
	v_exp_f32_e32 v238, v66
	v_exp_f32_e32 v239, v67
	v_pk_add_f32 v[66:67], v[96:97], v[210:211] op_sel_hi:[1,0] neg_lo:[0,1] neg_hi:[0,1]
	v_exp_f32_e32 v240, v68
	v_exp_f32_e32 v242, v66
	v_cvt_pk_bf16_f32 v66, v82, v83
	v_add_u32_e32 v82, s1, v1
	v_exp_f32_e32 v241, v69
	v_pk_add_f32 v[68:69], v[80:81], v[210:211] op_sel_hi:[1,0] neg_lo:[0,1] neg_hi:[0,1]
	v_add3_u32 v193, v82, v149, v154
	v_exp_f32_e32 v243, v67
	v_exp_f32_e32 v244, v68
	v_exp_f32_e32 v245, v69
	v_cvt_pk_bf16_f32 v67, v84, v85
	v_cvt_pk_bf16_f32 v68, v86, v87
	v_cvt_pk_bf16_f32 v69, v70, v71
	v_cvt_pk_bf16_f32 v70, v72, v73
	v_cvt_pk_bf16_f32 v71, v74, v75
	v_cvt_pk_bf16_f32 v72, v238, v239
	v_cvt_pk_bf16_f32 v73, v242, v243
	v_cvt_pk_bf16_f32 v74, v214, v215
	v_cvt_pk_bf16_f32 v75, v216, v217
	v_cvt_pk_bf16_f32 v76, v234, v235
	v_cvt_pk_bf16_f32 v77, v88, v89
	v_cvt_pk_bf16_f32 v78, v90, v91
	v_cvt_pk_bf16_f32 v79, v92, v93
	v_cvt_pk_bf16_f32 v80, v240, v241
	v_cvt_pk_bf16_f32 v81, v244, v245
	ds_read_b64_tr_b16 v[82:83], v193 offset:24576
	ds_read_b64_tr_b16 v[84:85], v193 offset:25088
	ds_read_b64_tr_b16 v[86:87], v193 offset:25600
	ds_read_b64_tr_b16 v[88:89], v193 offset:26112
	ds_read_b64_tr_b16 v[90:91], v193 offset:26624
	ds_read_b64_tr_b16 v[92:93], v193 offset:27136
	ds_read_b64_tr_b16 v[94:95], v193 offset:27648
	ds_read_b64_tr_b16 v[96:97], v193 offset:28160
	v_pk_add_f32 v[214:215], v[238:239], v[240:241]
	v_pk_add_f32 v[216:217], v[242:243], v[244:245]
	v_pk_add_f32 v[214:215], v[214:215], v[236:237]
	s_nop 0
	v_pk_add_f32 v[214:215], v[216:217], v[214:215]
	s_waitcnt lgkmcnt(6)
	v_mfma_f32_32x32x16_bf16 v[50:65], v[66:69], v[82:85], v[50:65]
	ds_read_b64_tr_b16 v[82:83], v193 offset:28672
	ds_read_b64_tr_b16 v[84:85], v193 offset:29184
	s_waitcnt lgkmcnt(6)
	v_mfma_f32_32x32x16_bf16 v[50:65], v[70:73], v[86:89], v[50:65]
	ds_read_b64_tr_b16 v[86:87], v193 offset:29696
	ds_read_b64_tr_b16 v[88:89], v193 offset:30208
	s_waitcnt lgkmcnt(6)
	v_mfma_f32_32x32x16_bf16 v[50:65], v[74:77], v[90:93], v[50:65]
	ds_read_b64_tr_b16 v[90:91], v193 offset:30720
	ds_read_b64_tr_b16 v[92:93], v193 offset:31232
	s_waitcnt lgkmcnt(6)
	v_mfma_f32_32x32x16_bf16 v[50:65], v[78:81], v[94:97], v[50:65]
	ds_read_b64_tr_b16 v[94:95], v193 offset:31744
	ds_read_b64_tr_b16 v[96:97], v193 offset:32256
	s_waitcnt lgkmcnt(6)
	v_mfma_f32_32x32x16_bf16 v[34:49], v[66:69], v[82:85], v[34:49]
	ds_read_b64_tr_b16 v[82:83], v193 offset:32768
	ds_read_b64_tr_b16 v[84:85], v193 offset:33280
	s_waitcnt lgkmcnt(6)
	v_mfma_f32_32x32x16_bf16 v[34:49], v[70:73], v[86:89], v[34:49]
	ds_read_b64_tr_b16 v[86:87], v193 offset:33792
	ds_read_b64_tr_b16 v[88:89], v193 offset:34304
	s_waitcnt lgkmcnt(6)
	v_mfma_f32_32x32x16_bf16 v[34:49], v[74:77], v[90:93], v[34:49]
	ds_read_b64_tr_b16 v[90:91], v193 offset:34816
	ds_read_b64_tr_b16 v[92:93], v193 offset:35328
	s_waitcnt lgkmcnt(6)
	v_mfma_f32_32x32x16_bf16 v[34:49], v[78:81], v[94:97], v[34:49]
	ds_read_b64_tr_b16 v[94:95], v193 offset:35840
	ds_read_b64_tr_b16 v[96:97], v193 offset:36352
	s_waitcnt lgkmcnt(6)
	v_mfma_f32_32x32x16_bf16 v[18:33], v[66:69], v[82:85], v[18:33]
	ds_read_b64_tr_b16 v[82:83], v193 offset:36864
	ds_read_b64_tr_b16 v[84:85], v193 offset:37376
	s_waitcnt lgkmcnt(6)
	v_mfma_f32_32x32x16_bf16 v[18:33], v[70:73], v[86:89], v[18:33]
	ds_read_b64_tr_b16 v[86:87], v193 offset:37888
	ds_read_b64_tr_b16 v[88:89], v193 offset:38400
	s_waitcnt lgkmcnt(6)
	v_mfma_f32_32x32x16_bf16 v[18:33], v[74:77], v[90:93], v[18:33]
	ds_read_b64_tr_b16 v[90:91], v193 offset:38912
	ds_read_b64_tr_b16 v[92:93], v193 offset:39424
	s_waitcnt lgkmcnt(6)
	v_mfma_f32_32x32x16_bf16 v[18:33], v[78:81], v[94:97], v[18:33]
	ds_read_b64_tr_b16 v[94:95], v193 offset:39936
	ds_read_b64_tr_b16 v[96:97], v193 offset:40448
	s_waitcnt lgkmcnt(6)
	v_mfma_f32_32x32x16_bf16 v[2:17], v[66:69], v[82:85], v[2:17]
	s_waitcnt lgkmcnt(4)
	v_mfma_f32_32x32x16_bf16 v[2:17], v[70:73], v[86:89], v[2:17]
	s_waitcnt lgkmcnt(2)
	v_mfma_f32_32x32x16_bf16 v[2:17], v[74:77], v[90:93], v[2:17]
	s_waitcnt lgkmcnt(0)
	v_mfma_f32_32x32x16_bf16 v[2:17], v[78:81], v[94:97], v[2:17]
	v_add_f32_e32 v66, v214, v215
	v_add_f32_e32 v232, v232, v66
	s_mov_b64 s[2:3], -1
	s_and_b64 vcc, exec, s[22:23]
	s_cbranch_vccnz .LBB0_721
